# GQA L0: stagger + all 8 K-fragment ds_reads issued up front into free VGPRs with counted lgkmcnt
# speedup vs baseline: 1.0018x; 1.0018x over previous
; template <int MODE>
; DI void attn_unit(char* lds, const Params& p, int layer, int u) {
;     ...
;   auto prefetch = [&](int t) __attribute__((always_inline)) {
;     const int key0 = (MODE == 3) ? q0 - 64 + 64 * t : 64 * (tlo + t);
;     if (MODE != 3) {
;       const size_t tokk = (size_t)(b * SEQ + key0 + srow);
;       const bf16_t* kp = (MODE == 0) ? p.proj + tokk * LDP + C_AK + h * 64 : (MODE == 1) ? p.knb + tokk * 256 + h * 64 : p.proj + tokk * LDP + C_CK + (h >> 1) * 64;
;       kr0 = *(const u32x4*)(kp + sc * 8);
;       if (MODE == 1) kr2 = *(const u32x4*)(p.proj + tokk * LDP + C_BKR + (sc & 3) * 8);
;       vr0 = *(const u32x4*)(vtbase + (size_t)srow * 4096 + key0 + sc * 8);
;     } else {
;       int v = key0 + srow; v = v < 0 ? 0 : (v >= L ? L - 1 : v);
;       const bf16_t* kp = p.proj + (size_t)(b * SEQ + rho + dl * v) * LDP + h * 64;
;       kr0 = *(const u32x4*)(kp + C_DK + sc * 8);
;       vr0 = *(const u32x4*)(kp + C_DV + sc * 8);
;     }
;   };
;   auto stage = [&](char* buf) __attribute__((always_inline)) {
;     char* kd = buf + srow * KST + sc * 16;
;     *(u32x4*)kd = kr0;
;     if (MODE == 1) { if (sc < 4) *(u32x4*)(buf + srow * KST + 128 + sc * 16) = kr2; }
;     if (MODE != 3) { *(u32x4*)(buf + VOFF + srow * VST + sc * 16) = vr0; }
;     ...
;   for (int t = 0; t < NT; ++t) {
;     char* cur = lds + (t & 1) * BUFSZ;
;     if (t + 1 < NT) { stage(lds + ((t + 1) & 1) * BUFSZ); if (t + 2 < NT) prefetch(t + 2); }
.LBB0_585:
	s_barrier
	s_cmp_eq_u32 s98, 0
	s_cbranch_scc0 .Lstg_g0_midB
	v_add_u32_e32 v242, s33, v94
	s_waitcnt vmcnt(1)
	ds_write_b128 v242, v[84:87]
	s_waitcnt vmcnt(0)
	ds_write_b128 v242, v[80:83] offset:9216
	s_nop 1
	v_mad_i64_i32 v[80:81], s[50:51], v101, s72, v[96:97]
	s_nop 1
	global_load_dwordx4 v[84:87], v[80:81], off offset:3328
	s_nop 0
	global_load_dwordx4 v[80:83], v[98:99], off

; DI f32x16 mfma32(bf16x8 a, bf16x8 b, f32x16 c) { return __builtin_amdgcn_mfma_f32_32x32x16_bf16(a, b, c, 0, 0, 0); }
; template <int MODE>
; DI void attn_unit(char* lds, const Params& p, int layer, int u) {
;     ...
;     if (t + 1 < NT) { stage(lds + ((t + 1) & 1) * BUFSZ); if (t + 2 < NT) prefetch(t + 2); }
;     const int key0 = (MODE == 3) ? q0 - 64 + 64 * t : 64 * (tlo + t);
;     const bool act = (MODE != 3) || (t >= (wid >> 1) && t <= (wid >> 1) + 2);
;     if (act) {
;       f32x16 S0 = zero16(), S1 = zero16();
;       const char* kb = cur + lr * KST + (MODE == 0 ? comp * 64 : 0) + lh * 16;
; #pragma unroll
;       for (int ks = 0; ks < NKS; ++ks) {
;         const bf16x8 k0 = *(const bf16x8*)(kb + ks * 32), k1 = *(const bf16x8*)(kb + 32 * KST + ks * 32);
;         S0 = mfma32(k0, qf[ks], S0); S1 = mfma32(k1, qf[ks], S1);
;       }
;       float aoff = 0.f;
;       if (MODE == 0) {
;         const float dbase = (float)(key0 + 4 * lh - qrow);
;         if (key0 > qlo + 31) { S0 = S0 - T0; S1 = S1 - T1; aoff = -slope2 * dbase; }
;         else if (key0 + 63 < qlo) { S0 = S0 + T0; S1 = S1 + T1; aoff = slope2 * dbase; }
;         else {
; #pragma unroll
;           for (int r = 0; r < 16; ++r) { const float cc = (float)((r & 3) + 8 * (r >> 2));
;             S0[r] = fmaf(-slope2, fabsf(dbase + cc), S0[r]); S1[r] = fmaf(-slope2, fabsf(dbase + cc + 32.f), S1[r]); }
;         }
;       }
;       if (MODE == 3) {
;         const int rel0 = key0 + 4 * lh - qrow;
; #pragma unroll
;         for (int r = 0; r < 16; ++r) { const int cc = (r & 3) + 8 * (r >> 2);
;           { const int rel = rel0 + cc, v = qrow + rel; const bool ok = (rel >= -64) && (rel <= 64) && (v >= 0) && (v < L); S0[r] = ok ? fmaf(-slope2, fabsf((float)rel), S0[r]) : -1e30f; }
;           { const int rel = rel0 + cc + 32, v = qrow + rel; const bool ok = (rel >= -64) && (rel <= 64) && (v >= 0) && (v < L); S1[r] = ok ? fmaf(-slope2, fabsf((float)rel), S1[r]) : -1e30f; } }
;       }
;       float mx = fmaxf(S0[0], S1[0]);
; #pragma unroll
;       for (int r = 1; r < 16; ++r) mx = max3f(mx, S0[r], S1[r]);
;       mx += aoff;
;       if (__any(mx > m + 8.f)) {
;         mx = fmaxf(mx, __shfl_xor(mx, 32));
;         const float mnew = fmaxf(m, mx);
;         const float al = __builtin_amdgcn_exp2f(m - mnew); l *= al; O0 *= al; O1 *= al;
;         m = mnew;
;       }
.LBB0_586:
	s_bitcmp1_b32 s1, 0
	s_cselect_b32 s4, 0, 0x4800
	s_cselect_b32 s33, 0x4800, 0
	v_add_u32_e32 v102, s4, v100
	v_add_u32_e32 v90, v102, v92
	s_cmp_eq_u32 s98, 0
	s_cbranch_scc1 .Lstg_g0_headA
	v_add_u32_e32 v242, s33, v94
	s_waitcnt vmcnt(1)
	ds_write_b128 v242, v[84:87]
	s_waitcnt vmcnt(0)
	ds_write_b128 v242, v[80:83] offset:9216
	ds_read_b128 v[210:213], v90
	ds_read_b128 v[214:217], v90 offset:4608
	v_mad_i64_i32 v[80:81], s[50:51], v101, s72, v[96:97]
	ds_read_b128 v[218:221], v90 offset:32
	global_load_dwordx4 v[84:87], v[80:81], off offset:3328
	s_nop 0
	global_load_dwordx4 v[80:83], v[98:99], off
	s_branch .Lstg_g0_qk
.Lstg_g0_headA:
	ds_read_b128 v[210:213], v90
	ds_read_b128 v[214:217], v90 offset:4608
	ds_read_b128 v[218:221], v90 offset:32
.Lstg_g0_qk:
	ds_read_b128 v[222:225], v90 offset:4640
	ds_read_b128 v[226:229], v90 offset:64
	ds_read_b128 v[230:233], v90 offset:4672
	ds_read_b128 v[234:237], v90 offset:96
	ds_read_b128 v[238:241], v90 offset:4704
	s_waitcnt lgkmcnt(7)
	v_mfma_f32_32x32x16_bf16 v[32:47], v[210:213], v[76:79], 0
	s_waitcnt lgkmcnt(6)
	v_mfma_f32_32x32x16_bf16 v[48:63], v[214:217], v[76:79], 0
	s_waitcnt lgkmcnt(5)
	v_mfma_f32_32x32x16_bf16 v[32:47], v[218:221], v[72:75], v[32:47]
	s_waitcnt lgkmcnt(4)
	v_mfma_f32_32x32x16_bf16 v[48:63], v[222:225], v[72:75], v[48:63]
	s_waitcnt lgkmcnt(3)
	v_mfma_f32_32x32x16_bf16 v[32:47], v[226:229], v[68:71], v[32:47]
	s_waitcnt lgkmcnt(2)
	v_mfma_f32_32x32x16_bf16 v[48:63], v[230:233], v[68:71], v[48:63]
	s_waitcnt lgkmcnt(1)
	v_mfma_f32_32x32x16_bf16 v[32:47], v[234:237], v[64:67], v[32:47]
	s_waitcnt lgkmcnt(0)
	v_mfma_f32_32x32x16_bf16 v[48:63], v[238:241], v[64:67], v[48:63]
	s_nop 9
	v_max_f32_e32 v91, v32, v32
	s_nop 0
	v_max_f32_e32 v90, v48, v48
	v_max_f32_e32 v90, v91, v90
	v_max3_f32 v90, v90, v33, v49
	v_add_f32_e32 v91, 0x41000000, v93
	v_max3_f32 v90, v90, v34, v50
	s_nop 0
	v_max3_f32 v90, v90, v35, v51
	s_nop 0
	v_max3_f32 v90, v90, v36, v52
	s_nop 0
	v_max3_f32 v90, v90, v37, v53
	s_nop 0
	v_max3_f32 v90, v90, v38, v54
	s_nop 0
	v_max3_f32 v90, v90, v39, v55
	s_nop 0
	v_max3_f32 v90, v90, v40, v56
	s_nop 0
	v_max3_f32 v90, v90, v41, v57
	s_nop 0
	v_max3_f32 v90, v90, v42, v58
	s_nop 0
	v_max3_f32 v90, v90, v43, v59
	s_nop 0
	v_max3_f32 v90, v90, v44, v60
	s_nop 0
	v_max3_f32 v90, v90, v45, v61
	s_nop 0
	v_max3_f32 v90, v90, v46, v62
	s_nop 0
	v_max3_f32 v90, v90, v47, v63
	s_nop 0
	v_cmp_gt_f32_e32 vcc, v90, v91
	s_cbranch_vccz .LBB0_585
	v_cmp_lt_i32_e32 vcc, v209, v208
	v_add_f32_e32 v90, 0, v90
	s_nop 0
	v_cndmask_b32_e32 v91, v207, v209, vcc
	v_lshlrev_b32_e32 v91, 2, v91
	ds_bpermute_b32 v91, v91, v90
	s_waitcnt lgkmcnt(0)
	v_max3_f32 v91, v93, v90, v91
	v_sub_f32_e32 v90, v93, v91
	v_exp_f32_e32 v90, v90
	v_mov_b32_e32 v93, v91
	v_mul_f32_e32 v95, v95, v90
	v_pk_mul_f32 v[14:15], v[14:15], v[90:91] op_sel_hi:[1,0]
	v_pk_mul_f32 v[12:13], v[12:13], v[90:91] op_sel_hi:[1,0]
	v_pk_mul_f32 v[10:11], v[10:11], v[90:91] op_sel_hi:[1,0]
	v_pk_mul_f32 v[8:9], v[8:9], v[90:91] op_sel_hi:[1,0]
	v_pk_mul_f32 v[6:7], v[6:7], v[90:91] op_sel_hi:[1,0]
	v_pk_mul_f32 v[4:5], v[4:5], v[90:91] op_sel_hi:[1,0]
	v_pk_mul_f32 v[2:3], v[2:3], v[90:91] op_sel_hi:[1,0]
	v_pk_mul_f32 v[0:1], v[0:1], v[90:91] op_sel_hi:[1,0]
	v_pk_mul_f32 v[30:31], v[30:31], v[90:91] op_sel_hi:[1,0]
	v_pk_mul_f32 v[28:29], v[28:29], v[90:91] op_sel_hi:[1,0]
	v_pk_mul_f32 v[26:27], v[26:27], v[90:91] op_sel_hi:[1,0]
	v_pk_mul_f32 v[24:25], v[24:25], v[90:91] op_sel_hi:[1,0]
	v_pk_mul_f32 v[22:23], v[22:23], v[90:91] op_sel_hi:[1,0]
	v_pk_mul_f32 v[20:21], v[20:21], v[90:91] op_sel_hi:[1,0]
	v_pk_mul_f32 v[18:19], v[18:19], v[90:91] op_sel_hi:[1,0]
	v_pk_mul_f32 v[16:17], v[16:17], v[90:91] op_sel_hi:[1,0]
	s_branch .LBB0_585
